# attention: key-norm bound computed once per (batch,head) by query block 0 and shared via workspace flag; other query blocks skip the K pre-pass
# speedup vs baseline: 1.0118x; 1.0118x over previous
.Lprio_done:
	v_and_b32_e32 v41, 15, v40
	v_lshl_or_b32 v0, v42, 4, v41
	s_add_i32 s24, s24, s25
	v_add_u32_e32 v104, s24, v0
	v_ashrrev_i32_e32 v105, 31, v104
	v_lshlrev_b64 v[0:1], 10, v[104:105]
	v_lshl_add_u64 v[0:1], s[4:5], 0, v[0:1]
	s_lshl_b32 s58, s35, 8
	v_lshl_add_u64 v[0:1], v[0:1], 0, s[58:59]
	v_and_b32_e32 v132, 48, v40
	v_lshl_add_u64 v[0:1], v[0:1], 0, v[132:133]
	s_mov_b64 s[4:5], 0xa2a4400
	v_lshl_add_u64 v[8:9], v[0:1], 0, s[4:5]
	s_mov_b32 s4, 0xa2a4000
	v_add_co_u32_e32 v10, vcc, s4, v0
	v_ashrrev_i32_e32 v36, 3, v40
	s_nop 0
	v_addc_co_u32_e32 v11, vcc, 0, v1, vcc
	global_load_dwordx4 v[0:3], v[8:9], off offset:64
	global_load_dwordx4 v[4:7], v[8:9], off offset:128
	global_load_dwordx4 v[12:15], v[10:11], off offset:1024
	s_nop 0
	global_load_dwordx4 v[8:11], v[8:9], off offset:192
	v_ashrrev_i32_e32 v37, 31, v36
	v_lshlrev_b64 v[34:35], 8, v[36:37]
	v_and_b32_e32 v37, 7, v40
	v_lshl_or_b32 v16, v37, 5, v34
	v_mov_b32_e32 v17, v35
	v_lshl_add_u64 v[32:33], s[18:19], 0, v[16:17]
	s_mov_b64 s[24:25], 0xc010
	v_and_b32_e32 v43, 63, v40
	v_bfe_u32 v105, v40, 4, 2
	s_lshl_b32 s22, s35, 7
	s_mov_b32 s4, 0
	s_lshr_b32 s23, s34, 6
	v_lshl_add_u64 v[38:39], v[32:33], 0, s[24:25]
	v_mov_b32_e32 v44, 0
	s_cmpk_lt_i32 s37, 0x100
	s_cselect_b32 s5, 15, 1
	s_and_b32 s5, s5, s37
	s_cmp_eq_u32 s5, 0
	s_cbranch_scc1 .LBB0_117
	s_lshr_b32 s24, s37, 4
	s_add_i32 s25, s37, 0xffffff00
	s_lshr_b32 s25, s25, 1
	s_add_i32 s25, s25, 16
	s_cmpk_lt_i32 s37, 0x100
	s_cselect_b32 s24, s24, s25
	s_mul_i32 s25, s40, 0x90
	s_add_i32 s24, s24, s25
	s_lshl_b32 s24, s24, 4
	s_add_u32 s24, s12, s24
	s_addc_u32 s25, s13, 0
	s_sub_u32 s24, s24, 0x9c02000
	s_subb_u32 s25, s25, 0
.Lkm_spin:
	global_load_dword v45, v133, s[24:25] sc1
	s_waitcnt vmcnt(0)
	v_readfirstlane_b32 s5, v45
	s_cmp_lg_u32 s5, 0
	s_cbranch_scc1 .Lkm_ready
	s_sleep 4
	s_branch .Lkm_spin
.Lkm_ready:
	global_load_dwordx2 v[46:47], v133, s[24:25] offset:8 sc1
	v_and_b32_e32 v45, 4, v40
	v_cmp_ne_u32_e32 vcc, 0, v45
	s_waitcnt vmcnt(0)
	s_nop 1
	v_cndmask_b32_e32 v44, v46, v47, vcc
	s_branch .Lkm_skip_loop

.Lkm_skip_loop:
	v_lshlrev_b32_e32 v17, 2, v43
	v_xor_b32_e32 v16, 32, v17
	ds_bpermute_b32 v18, v16, v44
	v_max_f32_e32 v19, v44, v44
	v_xor_b32_e32 v114, 64, v17
	v_xor_b32_e32 v115, 0x80, v17
	v_and_b32_e32 v20, 59, v40
	s_waitcnt lgkmcnt(0)
	v_max_f32_e32 v18, v18, v18
	v_max_f32_e32 v18, v19, v18
	ds_bpermute_b32 v19, v114, v18
	v_cmp_eq_u32_e32 vcc, 0, v20
	s_waitcnt lgkmcnt(0)
	s_barrier
	v_max_f32_e32 v19, v19, v19
	v_max_f32_e32 v18, v18, v19
	ds_bpermute_b32 v19, v115, v18
	s_and_saveexec_b64 s[4:5], vcc
	s_cbranch_execz .LBB0_120
	s_waitcnt lgkmcnt(0)
	v_max_f32_e32 v19, v19, v19
	v_max_f32_e32 v18, v18, v18
	v_max_f32_e32 v18, v18, v19
	v_lshlrev_b32_e32 v19, 3, v42
	v_add3_u32 v19, s69, v19, v43
	ds_write_b32 v19, v18
.LBB0_120:
	s_or_b64 exec, exec, s[4:5]
	v_readlane_b32 s4, v254, 9
	v_mov_b32_e32 v18, s69
	s_waitcnt lgkmcnt(0)
	v_mov_b32_e32 v19, s4
	s_barrier
	ds_read_b32 v18, v18
	ds_read_b32 v19, v19
	v_readlane_b32 s4, v254, 10
	v_and_b32_e32 v22, 0xffff0000, v13
	v_mul_f32_e32 v22, v22, v22
	s_waitcnt lgkmcnt(1)
	v_max_f32_e32 v18, v18, v18
	s_waitcnt lgkmcnt(0)
	v_max_f32_e32 v19, v19, v19
	v_max_f32_e32 v18, v18, v19
	v_mov_b32_e32 v19, s4
	v_readlane_b32 s4, v254, 11
	ds_read_b32 v19, v19
	s_mov_b32 s24, 0xf800000
	v_mov_b32_e32 v20, s4
	ds_read_b32 v20, v20
	v_readlane_b32 s4, v254, 12
	s_waitcnt lgkmcnt(0)
	v_max3_f32 v18, v18, v19, v20
	v_mov_b32_e32 v19, s4
	v_readlane_b32 s4, v254, 13
	ds_read_b32 v19, v19
	s_nop 0
	v_mov_b32_e32 v20, s4
	ds_read_b32 v20, v20
	v_readlane_b32 s4, v254, 14
	s_waitcnt lgkmcnt(0)
	v_max3_f32 v18, v18, v19, v20
	v_mov_b32_e32 v19, s4
	v_readlane_b32 s4, v254, 15
	ds_read_b32 v19, v19
	s_nop 0
	v_mov_b32_e32 v20, s4
	ds_read_b32 v20, v20
	v_readlane_b32 s4, v254, 16
	s_waitcnt lgkmcnt(0)
	v_max3_f32 v18, v18, v19, v20
	v_mov_b32_e32 v19, s4
	v_readlane_b32 s4, v254, 17
	ds_read_b32 v19, v19
	s_waitcnt lgkmcnt(0)
	v_max_f32_e32 v19, v19, v19
	v_mov_b32_e32 v20, s4
	ds_read_b32 v20, v20
	v_readlane_b32 s4, v254, 18
	s_waitcnt lgkmcnt(0)
	v_max_f32_e32 v20, v20, v20
	v_max_f32_e32 v19, v19, v20
	v_mov_b32_e32 v20, s4
	v_readlane_b32 s4, v254, 19
	ds_read_b32 v20, v20
	s_nop 0
	v_mov_b32_e32 v21, s4
	ds_read_b32 v21, v21
	v_readlane_b32 s4, v254, 20
	s_waitcnt lgkmcnt(0)
	v_max3_f32 v19, v19, v20, v21
	v_mov_b32_e32 v20, s4
	v_readlane_b32 s4, v254, 21
	ds_read_b32 v20, v20
	s_nop 0
	v_mov_b32_e32 v21, s4
	ds_read_b32 v21, v21
	v_readlane_b32 s4, v254, 22
	s_waitcnt lgkmcnt(0)
	v_max3_f32 v19, v19, v20, v21
	v_mov_b32_e32 v20, s4
	v_readlane_b32 s4, v254, 23
	ds_read_b32 v20, v20
	s_nop 0
	v_mov_b32_e32 v21, s4
	ds_read_b32 v21, v21
	s_waitcnt lgkmcnt(0)
	s_barrier
	v_max3_f32 v20, v19, v20, v21
	s_cmpk_lt_i32 s37, 0x100
	s_cselect_b32 s25, 15, 1
	s_and_b32 s25, s25, s37
	s_cmp_lg_u32 s25, 0
	s_cbranch_scc1 .Lkm_nopub
	s_lshr_b32 s4, s37, 4
	s_add_i32 s5, s37, 0xffffff00
	s_lshr_b32 s5, s5, 1
	s_add_i32 s5, s5, 16
	s_cmpk_lt_i32 s37, 0x100
	s_cselect_b32 s4, s4, s5
	s_mul_i32 s5, s40, 0x90
	s_add_i32 s4, s4, s5
	s_lshl_b32 s4, s4, 4
	s_add_u32 s4, s12, s4
	s_addc_u32 s5, s13, 0
	s_sub_u32 s4, s4, 0x9c02000
	s_subb_u32 s5, s5, 0
	v_cmp_eq_u32_e32 vcc, 0, v40
	s_and_b64 exec, exec, vcc
	v_mov_b32_e32 v46, v18
	v_mov_b32_e32 v47, v20
	global_store_dwordx2 v133, v[46:47], s[4:5] offset:8 sc1
	s_waitcnt vmcnt(0)
	v_mov_b32_e32 v45, 1
	global_store_dword v133, v45, s[4:5] sc1
	s_mov_b64 exec, -1
.Lkm_nopub:
	v_and_b32_e32 v21, 0xffff0000, v12
	v_lshlrev_b32_e32 v19, 16, v12
	v_mul_f32_e32 v21, v21, v21
	v_fmac_f32_e32 v21, v19, v19
	v_lshlrev_b32_e32 v19, 16, v13
	v_fmac_f32_e32 v22, v19, v19
	v_add_f32_e32 v19, v21, v22
	v_and_b32_e32 v22, 0xffff0000, v14
	v_lshlrev_b32_e32 v21, 16, v14
	v_mul_f32_e32 v22, v22, v22
	v_fmac_f32_e32 v22, v21, v21
	v_add_f32_e32 v19, v22, v19
	v_and_b32_e32 v22, 0xffff0000, v15
	v_lshlrev_b32_e32 v21, 16, v15
	v_mul_f32_e32 v22, v22, v22
	v_fmac_f32_e32 v22, v21, v21
	v_add_f32_e32 v19, v22, v19
	v_and_b32_e32 v22, 0xffff0000, v0
	v_lshlrev_b32_e32 v21, 16, v0
	v_mul_f32_e32 v22, v22, v22
	v_fmac_f32_e32 v22, v21, v21
	v_add_f32_e32 v19, v22, v19
	v_and_b32_e32 v22, 0xffff0000, v1
	v_lshlrev_b32_e32 v21, 16, v1
	v_mul_f32_e32 v22, v22, v22
	v_fmac_f32_e32 v22, v21, v21
	v_add_f32_e32 v19, v22, v19
	v_and_b32_e32 v22, 0xffff0000, v2
	v_lshlrev_b32_e32 v21, 16, v2
	v_mul_f32_e32 v22, v22, v22
	v_fmac_f32_e32 v22, v21, v21
	v_add_f32_e32 v19, v22, v19
	v_and_b32_e32 v22, 0xffff0000, v3
	v_lshlrev_b32_e32 v21, 16, v3
	v_mul_f32_e32 v22, v22, v22
	v_fmac_f32_e32 v22, v21, v21
	v_add_f32_e32 v19, v22, v19
	ds_bpermute_b32 v21, v114, v19
	s_waitcnt lgkmcnt(0)
	v_add_f32_e32 v19, v19, v21
	ds_bpermute_b32 v21, v115, v19
	s_waitcnt lgkmcnt(0)
	v_add_f32_e32 v19, v19, v21
	v_mul_f32_e32 v18, v18, v19
	v_cmp_gt_f32_e32 vcc, s24, v18
	v_mul_f32_e32 v19, 0x4f800000, v18
	s_nop 0
	v_cndmask_b32_e32 v18, v18, v19, vcc
	v_sqrt_f32_e32 v19, v18
	s_nop 0
	v_add_u32_e32 v21, -1, v19
	v_fma_f32 v22, -v21, v19, v18
	v_cmp_ge_f32_e64 s[4:5], 0, v22
	v_add_u32_e32 v22, 1, v19
	s_nop 0
	v_cndmask_b32_e64 v21, v19, v21, s[4:5]
	v_fma_f32 v19, -v22, v19, v18
	v_cmp_lt_f32_e64 s[4:5], 0, v19
	s_nop 1
	v_cndmask_b32_e64 v19, v21, v22, s[4:5]
	v_mul_f32_e32 v21, 0x37800000, v19
	v_cndmask_b32_e32 v19, v19, v21, vcc
	v_cmp_class_f32_e32 vcc, v18, v193
	v_and_b32_e32 v21, 0xffff0000, v4
	v_mul_f32_e32 v21, v21, v21
	v_cndmask_b32_e32 v18, v19, v18, vcc
	v_fmamk_f32 v19, v18, 0x3f8020c5, v194
	v_lshlrev_b32_e32 v18, 16, v4
	v_and_b32_e32 v22, 0xffff0000, v5
	v_fmac_f32_e32 v21, v18, v18
	v_lshlrev_b32_e32 v18, 16, v5
	v_mul_f32_e32 v22, v22, v22
	v_fmac_f32_e32 v22, v18, v18
	v_add_f32_e32 v18, v21, v22
	v_and_b32_e32 v22, 0xffff0000, v6
	v_lshlrev_b32_e32 v21, 16, v6
	v_mul_f32_e32 v22, v22, v22
	v_fmac_f32_e32 v22, v21, v21
	v_add_f32_e32 v18, v22, v18
	v_and_b32_e32 v22, 0xffff0000, v7
	v_lshlrev_b32_e32 v21, 16, v7
	v_mul_f32_e32 v22, v22, v22
	v_fmac_f32_e32 v22, v21, v21
	v_add_f32_e32 v18, v22, v18
	v_and_b32_e32 v22, 0xffff0000, v8
	v_lshlrev_b32_e32 v21, 16, v8
	v_mul_f32_e32 v22, v22, v22
	v_fmac_f32_e32 v22, v21, v21
	v_add_f32_e32 v18, v22, v18
	v_and_b32_e32 v22, 0xffff0000, v9
	v_lshlrev_b32_e32 v21, 16, v9
	v_mul_f32_e32 v22, v22, v22
	v_fmac_f32_e32 v22, v21, v21
	v_add_f32_e32 v18, v22, v18
	v_and_b32_e32 v22, 0xffff0000, v10
	v_lshlrev_b32_e32 v21, 16, v10
	v_mul_f32_e32 v22, v22, v22
	v_fmac_f32_e32 v22, v21, v21
	v_add_f32_e32 v18, v22, v18
	v_and_b32_e32 v22, 0xffff0000, v11
	v_lshlrev_b32_e32 v21, 16, v11
	v_mul_f32_e32 v22, v22, v22
	v_fmac_f32_e32 v22, v21, v21
	v_add_f32_e32 v18, v22, v18
	ds_bpermute_b32 v21, v114, v18
	s_waitcnt lgkmcnt(0)
	v_add_f32_e32 v18, v18, v21
	ds_bpermute_b32 v21, v115, v18
	s_waitcnt lgkmcnt(0)
	v_add_f32_e32 v18, v18, v21
	v_mul_f32_e32 v18, v20, v18
	v_cmp_gt_f32_e32 vcc, s24, v18
	v_mul_f32_e32 v20, 0x4f800000, v18
	s_nop 0
	v_cndmask_b32_e32 v18, v18, v20, vcc
	v_sqrt_f32_e32 v20, v18
	s_nop 0
	v_add_u32_e32 v21, -1, v20
	v_fma_f32 v22, -v21, v20, v18
	v_cmp_ge_f32_e64 s[4:5], 0, v22
	v_add_u32_e32 v22, 1, v20
	s_nop 0
	v_cndmask_b32_e64 v21, v20, v21, s[4:5]
	v_fma_f32 v20, -v22, v20, v18
	v_cmp_lt_f32_e64 s[4:5], 0, v20
	s_nop 1
	v_cndmask_b32_e64 v20, v21, v22, s[4:5]
	v_mul_f32_e32 v21, 0x37800000, v20
	v_cndmask_b32_e32 v20, v20, v21, vcc
	v_cmp_class_f32_e32 vcc, v18, v193
	v_xor_b32_e32 v21, 4, v17
	s_nop 0
	v_cndmask_b32_e32 v18, v20, v18, vcc
	v_fmamk_f32 v20, v18, 0x3f8020c5, v194
	v_max3_f32 v18, v19, 0, v20
	ds_bpermute_b32 v21, v21, v18
	v_cmp_eq_u32_e32 vcc, 0, v43
	s_waitcnt lgkmcnt(0)
	v_max_f32_e32 v21, v21, v21
	v_max_f32_e32 v18, v18, v21
	v_xor_b32_e32 v21, 8, v17
	ds_bpermute_b32 v21, v21, v18
	v_xor_b32_e32 v17, 16, v17
	s_waitcnt lgkmcnt(0)
	v_max_f32_e32 v21, v21, v21
	v_max_f32_e32 v18, v18, v21
	ds_bpermute_b32 v17, v17, v18
	s_waitcnt lgkmcnt(0)
	v_max_f32_e32 v17, v17, v17
	v_max_f32_e32 v17, v18, v17
	ds_bpermute_b32 v16, v16, v17
	s_and_saveexec_b64 s[4:5], vcc
	s_cbranch_execz .LBB0_122
	s_waitcnt lgkmcnt(0)
	v_max_f32_e32 v16, v16, v16
	v_max_f32_e32 v17, v17, v17
	v_max_f32_e32 v16, v17, v16
	v_lshl_add_u32 v17, v42, 2, s69
	ds_write_b32 v17, v16 offset:64
